# q-projection item no longer waits for the previous item's stores before its entry barrier
# baseline (speedup 1.0000x reference)
; template <int WN, int WT>
; DEV void gemm_mainloop(const u16* __restrict__ Wt, long ldw, const u16* __restrict__ A, long lda, int K,
;                        char* smem, int tid, f32x4 (&acc)[WN][WT]) {
;     ...
;   __syncthreads();
;   stage_tile<NR>(Wt, ldw, 0, smem, tid);
;   stage_tile<TR>(A, lda, 0, smem + WB, tid);
;   if (nk > 1) {
;     stage_tile<NR>(Wt, ldw, 64, smem + STG, tid);
;     stage_tile<TR>(A, lda, 64, smem + STG + WB, tid);
;   }
; DEV void qproj_item(const Params& p, int l, int tt, int tf, char* smem, int tid) {
;   const int t0 = tt * 192, f0 = tf * 128;
;   f32x4 acc[2][6];
;   zero_acc<2, 6>(acc);
;   float* rs = (float*)(smem + 122880);
;   __syncthreads();
;   row_scales(p.z + (long)t0 * NINP, C_CQ, 256, rs, tid);
;   gemm_mainloop<2, 6>(p.WuqT + ((long)l * 768 + f0) * 256, 256, p.z + (long)t0 * NINP + C_CQ, NINP, 256, smem, tid, acc);
.LBB0_767:
	s_mul_i32 s6, s15, 43
	s_lshr_b32 s16, s6, 8
	s_mul_i32 s6, s16, 6
	s_sub_i32 s10, s15, s6
	s_cmp_eq_u32 s16, 0
	v_readlane_b32 s8, v255, 42
	s_cselect_b64 s[6:7], -1, 0
	v_readlane_b32 s9, v255, 43
	s_and_b64 s[6:7], s[8:9], s[6:7]
	s_and_b64 vcc, exec, s[6:7]
	s_cbranch_vccnz .LBB0_749
	v_readlane_b32 s6, v255, 10
	s_add_i32 s16, s16, s6
	s_mul_i32 s17, s16, 0xc0
	s_movk_i32 s8, 0x180
	s_mul_i32 s6, s16, 0x330000
	s_mul_hi_i32 s7, s17, 0x4400
	v_cmp_gt_i32_e32 vcc, s8, v58
	s_barrier
	v_and_b32_e32 v132, 0xff, v197
	v_lshlrev_b32_e32 v132, 4, v132
	global_load_dwordx4 v[128:131], v132, s[82:83]
	s_lshl_b32 s8, s10, 7
	s_add_u32 s10, s88, s6
	s_addc_u32 s11, s89, s7
	s_ashr_i32 s9, s8, 31
	s_mul_i32 s18, s14, 0x300
	s_add_u32 s18, s8, s18
	s_addc_u32 s19, s9, 0
	v_readlane_b32 s40, v253, 7
	v_lshrrev_b32_e32 v18, 4, v58
	v_ashrrev_i32_e32 v2, 3, v58
	s_lshl_b64 s[18:19], s[18:19], 9
	v_readlane_b32 s46, v253, 13
	s_waitcnt lgkmcnt(0)
	v_xor_b32_e32 v0, v18, v58
	v_ashrrev_i32_e32 v3, 31, v2
	v_readlane_b32 s47, v253, 14
	s_add_u32 s18, s46, s18
	v_lshlrev_b32_e32 v0, 4, v0
	v_lshlrev_b64 v[4:5], 9, v[2:3]
	v_add_u32_e32 v3, 0x200, v58
	s_addc_u32 s19, s47, s19
	v_and_b32_e32 v156, 0x70, v0
	v_lshlrev_b32_e32 v59, 4, v58
	v_ashrrev_i32_e32 v8, 3, v3
	v_lshl_add_u64 v[0:1], s[18:19], 0, v[156:157]
	v_readfirstlane_b32 s18, v59
	v_ashrrev_i32_e32 v9, 31, v8
	v_lshlrev_b32_e32 v60, 4, v3
	v_lshl_add_u64 v[12:13], s[10:11], 0, v[156:157]
	v_lshl_add_u64 v[6:7], v[0:1], 0, v[4:5]
	s_mov_b32 m0, s18
	v_lshlrev_b64 v[10:11], 9, v[8:9]
	v_readfirstlane_b32 s18, v60
	v_mad_i64_i32 v[14:15], s[10:11], v2, s33, v[12:13]
	v_add_u32_e32 v3, 0x4000, v59
	s_barrier
	global_load_lds_dwordx4 v[6:7], off
	v_lshl_add_u64 v[0:1], v[0:1], 0, v[10:11]
	s_mov_b32 m0, s18
	v_readfirstlane_b32 s10, v3
	global_load_lds_dwordx4 v[0:1], off
	s_mov_b32 m0, s10
	v_mad_i64_i32 v[16:17], s[10:11], v8, s33, v[12:13]
	v_add_u32_e32 v3, 0x4000, v60
	global_load_lds_dwordx4 v[14:15], off
	v_readfirstlane_b32 s10, v3
	v_add_u32_e32 v3, 0x400, v58
	v_ashrrev_i32_e32 v9, 3, v3
	v_lshlrev_b32_e32 v61, 4, v3
	s_mov_b32 m0, s10
	v_mad_i64_i32 v[12:13], s[10:11], v9, s33, v[12:13]
	v_add_u32_e32 v3, 0x4000, v61
	global_load_lds_dwordx4 v[16:17], off
	v_readfirstlane_b32 s10, v3
	v_add_u32_e32 v3, 0xa000, v59
	s_mov_b32 m0, s10
	v_readfirstlane_b32 s10, v3
	v_add_u32_e32 v3, 0xa000, v60
	global_load_lds_dwordx4 v[12:13], off
	v_lshl_add_u64 v[6:7], v[6:7], 0, s[34:35]
	s_mov_b32 m0, s10
	v_readfirstlane_b32 s10, v3
	v_add_u32_e32 v3, 0xe000, v59
	global_load_lds_dwordx4 v[6:7], off
	v_lshl_add_u64 v[0:1], v[0:1], 0, s[34:35]
	s_mov_b32 m0, s10
	v_readfirstlane_b32 s10, v3
	v_add_u32_e32 v3, 0xe000, v60
	global_load_lds_dwordx4 v[0:1], off
	v_lshl_add_u64 v[0:1], v[14:15], 0, s[34:35]
	s_mov_b32 m0, s10
	v_readfirstlane_b32 s10, v3
	v_add_u32_e32 v3, 0xe000, v61
	global_load_lds_dwordx4 v[0:1], off
	v_lshl_add_u64 v[0:1], v[16:17], 0, s[34:35]
	s_mov_b32 m0, s10
	v_readfirstlane_b32 s10, v3
	global_load_lds_dwordx4 v[0:1], off
	v_lshl_add_u64 v[0:1], v[12:13], 0, s[34:35]
	s_mov_b32 m0, s10
	v_lshrrev_b32_e32 v63, 1, v58
	global_load_lds_dwordx4 v[0:1], off
	s_mov_b32 s98, s8
	s_mov_b32 s99, s9
	v_mov_b32_e32 v133, v2
	v_mov_b32_e32 v134, v4
	v_mov_b32_e32 v135, v5
	s_and_saveexec_b64 s[8:9], vcc
	s_cbranch_execz .LBB0_773
	v_ashrrev_i32_e32 v2, 1, v58
	v_mov_b64_e32 v[0:1], s[6:7]
	v_mad_i64_i32 v[0:1], s[18:19], v2, s33, v[0:1]
	v_and_b32_e32 v3, 1, v58
	v_lshlrev_b32_e32 v156, 8, v3
	v_readlane_b32 s18, v254, 37
	v_lshl_add_u64 v[0:1], v[0:1], 0, v[156:157]
	v_readlane_b32 s19, v254, 38
	v_mov_b32_e32 v4, 0
	s_mov_b32 s11, -8
	v_lshl_add_u64 v[0:1], s[18:19], 0, v[0:1]
